# v84 + band item prologue de-serialised: bias-table load, sink load, Q and first-tile loads all in flight under one wait
# speedup vs baseline: 1.0128x; 1.0005x over previous
; DI void band_item(const Params& P, char* lds_blk, int layer, int bp) {
;     ...
;     float* btab = (float*)(lds + 4 * 64 * GP);
;     const float* tabg = (const float*)(P.ws + WS_TABB) + (type * 12 + head) * 384;
;     for (int i = tid; i < 384; i += 256) btab[i] = tabg[i];
;     bf16x8 qf[4];
; #pragma unroll
;     for (int s = 0; s < 4; ++s) qf[s] = *(const bf16x8*)(qp + (size_t)(32 * w + r) * rs + 16 * s + 8 * h);
;     float m = -1e30f, l = 0.f;
;     if (type == 0) { m = P.sinks[layer * 12 + head] * LOG2E; l = (h == 0) ? 1.f : 0.f; }
;     f32x16 O[2];
; #pragma unroll
;     for (int dt = 0; dt < 2; ++dt)
; #pragma unroll
;         for (int i = 0; i < 16; ++i) O[dt][i] = 0.f;
;     const int maxd = type == 0 ? 127 : 128;
;     const int qpos = 128 + 32 * w + r;
;     const int kt0 = (nb == 0 ? 2 : 0);
.LBB0_207:
	s_and_b32 s55, 0xffff, s50
	v_mad_u64_u32 v[8:9], s[22:23], s55, 12, v[108:109]
	s_movk_i32 s22, 0x180
	s_nop 0
	v_mul_lo_u32 v8, v8, s22
	v_mul_i32_i24_e32 v14, 0xa000, v0
	v_ashrrev_i32_e32 v9, 31, v8
	v_lshlrev_b32_sdwa v0, v188, v10 dst_sel:DWORD dst_unused:UNUSED_PAD src0_sel:DWORD src1_sel:BYTE_0
	v_or_b32_e32 v3, v14, v0
	s_movk_i32 s22, 0xff00
	v_lshl_add_u64 v[8:9], v[8:9], 2, v[0:1]
	v_add_u32_e32 v3, s69, v3
	v_or_b32_sdwa v5, v10, s22 dst_sel:DWORD dst_unused:UNUSED_PAD src0_sel:BYTE_0 src1_sel:DWORD
	v_lshl_add_u64 v[8:9], s[12:13], 0, v[8:9]
	global_load_dword v136, v[8:9], off
	v_mov_b32_e32 v137, v3
	v_and_b32_e32 v139, 0x80, v174
	v_cmp_eq_u32_e32 vcc, 0, v139
	s_and_saveexec_b64 s[22:23], vcc
	global_load_dword v139, v[8:9], off offset:1024
	s_or_b64 exec, exec, s[22:23]
	v_sub_co_u32_e32 v0, vcc, s63, v189
	s_and_b32 s64, s16, 63
	v_readfirstlane_b32 s22, v0
	s_cmpk_lt_u32 s22, 0x300
	s_cselect_b64 s[22:23], -1, 0
	s_and_b64 s[50:51], s[22:23], exec
	s_cselect_b32 s65, 2, 4
	s_and_b64 s[50:51], vcc, exec
	s_cselect_b32 s50, 0, s65
	s_lshr_b32 s51, 64, s50
	s_xor_b32 s65, s50, 6
	s_add_i32 s51, s51, -1
	s_lshr_b32 s65, s64, s65
	s_and_b32 s64, s51, s64
	s_cmpk_gt_u32 s16, 0x17f
	s_cselect_b32 s70, 0x2000, 0
	s_or_b32 s16, s65, s70
	s_and_b64 s[72:73], s[22:23], exec
	s_cselect_b32 s51, 9, 11
	s_and_b64 s[72:73], vcc, exec
	s_cselect_b32 s51, 7, s51
	s_lshl_b32 s71, s64, s51
	s_add_i32 s51, s71, s16
	v_lshrrev_b32_sdwa v122, v190, v10 dst_sel:DWORD dst_unused:UNUSED_PAD src0_sel:DWORD src1_sel:BYTE_0
	s_and_b64 s[22:23], s[22:23], exec
	s_mul_i32 s73, s51, 0x3800
	v_and_b32_e32 v123, 31, v10
	s_cselect_b32 s72, s43, 0x1c000
	s_and_b64 s[22:23], vcc, exec
	v_lshlrev_b32_e32 v111, 5, v122
	s_mul_hi_u32 s16, s51, 0x3800
	s_cselect_b32 s72, 0x1c00, s72
	s_add_u32 s22, s34, s73
	v_or_b32_e32 v109, v111, v123
	v_ashrrev_i32_e32 v3, 31, v2
	s_addc_u32 s23, s35, s16
	v_mul_u32_u24_e32 v0, s72, v109
	v_bfe_u32 v8, v10, 5, 1
	v_lshl_add_u64 v[2:3], v[2:3], 1, s[22:23]
	v_lshlrev_b32_e32 v0, 1, v0
	v_lshl_add_u64 v[2:3], v[2:3], 0, v[0:1]
	v_lshlrev_b32_e32 v112, 4, v8
	v_mov_b32_e32 v113, v1
	v_lshl_add_u64 v[2:3], v[2:3], 0, v[112:113]
	flat_load_dwordx4 v[66:69], v[2:3]
	flat_load_dwordx4 v[70:73], v[2:3] offset:32
	flat_load_dwordx4 v[74:77], v[2:3] offset:64
	flat_load_dwordx4 v[78:81], v[2:3] offset:96
	v_and_b32_e32 v107, 63, v10
	v_mov_b32_e32 v2, 0
	s_and_b64 vcc, exec, s[0:1]
	s_cbranch_vccz .LBB0_211
	v_add_u32_e32 v12, s27, v108
	v_ashrrev_i32_e32 v13, 31, v12
	v_lshl_add_u64 v[12:13], v[12:13], 2, s[30:31]
	global_load_dword v138, v[12:13], off
	v_cmp_gt_u32_e32 vcc, 32, v107
	s_movk_i32 s0, 0xff81
	s_nop 1
	v_cndmask_b32_e64 v124, 0, 1.0, vcc
	s_branch .LBB0_212

; DI void band_item(const Params& P, char* lds_blk, int layer, int bp) {
;     ...
;     float* btab = (float*)(lds + 4 * 64 * GP);
;     const float* tabg = (const float*)(P.ws + WS_TABB) + (type * 12 + head) * 384;
;     for (int i = tid; i < 384; i += 256) btab[i] = tabg[i];
;     bf16x8 qf[4];
; #pragma unroll
;     for (int s = 0; s < 4; ++s) qf[s] = *(const bf16x8*)(qp + (size_t)(32 * w + r) * rs + 16 * s + 8 * h);
;     float m = -1e30f, l = 0.f;
;     if (type == 0) { m = P.sinks[layer * 12 + head] * LOG2E; l = (h == 0) ? 1.f : 0.f; }
;     f32x16 O[2];
; #pragma unroll
;     for (int dt = 0; dt < 2; ++dt)
; #pragma unroll
;         for (int i = 0; i < 16; ++i) O[dt][i] = 0.f;
;     const int maxd = type == 0 ? 127 : 128;
;     const int qpos = 128 + 32 * w + r;
;     const int kt0 = (nb == 0 ? 2 : 0);
;     u32x4 rk[2], rv[2];
;     const int srow = tid >> 3, sch = tid & 7;
;     auto gload = [&](int kt) {
; #pragma unroll
;         for (int j = 0; j < 2; ++j) {
;             const ptrdiff_t ro = ((ptrdiff_t)(64 * kt + srow + 32 * j) - 128) * (ptrdiff_t)rs + sch * 8;
;             rk[j] = *(const u32x4*)(kp + ro); rv[j] = *(const u32x4*)(vp + ro);
;         }
;     };
;     auto lstore = [&](int b) {
;         char* sK = lds + b * (2 * 64 * GP); char* sV = sK + 64 * GP;
; #pragma unroll
;         for (int j = 0; j < 2; ++j) { *(u32x4*)(sK + (srow + 32 * j) * GP + sch * 16) = rk[j]; *(u32x4*)(sV + (srow + 32 * j) * GP + sch * 16) = rv[j]; }
;     };
;     gload(kt0); lstore(0);
.LBB0_212:
	s_cmp_eq_u32 s64, 0
	s_cselect_b32 s1, 2, 1
	s_cselect_b32 s100, 0, 1
	v_lshrrev_b32_sdwa v0, v191, v10 dst_sel:DWORD dst_unused:UNUSED_PAD src0_sel:DWORD src1_sel:BYTE_0
	s_lshl_b32 s64, s1, 6
	v_or_b32_e32 v15, s64, v0
	v_and_b32_e32 v113, 7, v10
	v_add_u32_e32 v3, 0xffffff80, v15
	v_mul_hi_i32_i24_e32 v13, s72, v3
	v_mul_i32_i24_e32 v12, s72, v3
	v_lshlrev_b32_e32 v110, 3, v113
	s_lshl_b32 s16, s72, 5
	v_ashrrev_i32_e32 v5, 31, v4
	v_or_b32_e32 v20, v12, v110
	v_mov_b32_e32 v21, v13
	v_lshl_add_u64 v[12:13], v[12:13], 0, s[16:17]
	v_ashrrev_i32_e32 v7, 31, v6
	v_lshlrev_b64 v[16:17], 1, v[4:5]
	v_or_b32_e32 v12, v12, v110
	v_lshl_add_u64 v[4:5], s[22:23], 0, v[16:17]
	v_lshlrev_b64 v[18:19], 1, v[6:7]
	v_lshlrev_b64 v[20:21], 1, v[20:21]
	v_lshlrev_b64 v[12:13], 1, v[12:13]
	v_lshl_add_u64 v[6:7], s[22:23], 0, v[18:19]
	v_lshl_add_u64 v[22:23], v[4:5], 0, v[20:21]
	v_lshl_add_u64 v[4:5], v[4:5], 0, v[12:13]
	v_lshl_add_u64 v[20:21], v[6:7], 0, v[20:21]
	flat_load_dwordx4 v[82:85], v[22:23]
	flat_load_dwordx4 v[86:89], v[20:21]
	v_lshl_add_u64 v[6:7], v[6:7], 0, v[12:13]
	flat_load_dwordx4 v[90:93], v[4:5]
	flat_load_dwordx4 v[94:97], v[6:7]
	v_add_u32_e32 v20, s0, v111
	v_lshlrev_b32_e32 v21, 2, v8
	v_lshrrev_b32_e32 v23, 2, v10
	v_add_u32_e32 v26, v111, v123
	s_add_i32 s0, s70, s65
	v_or_b32_e32 v22, 32, v107
	v_and_b32_e32 v24, 16, v10
	v_lshlrev_b32_e32 v25, 2, v107
	v_add_u32_e32 v128, 0x80, v20
	v_and_or_b32 v20, v23, 3, v21
	v_sub_u32_e32 v21, v26, v21
	s_add_i32 s0, s0, s71
	v_mul_u32_u24_e32 v129, 0x90, v22
	v_and_or_b32 v22, v25, 12, v24
	v_mul_u32_u24_e32 v131, 0x90, v20
	s_add_i32 s65, s1, -1
	v_subrev_u32_e32 v20, s64, v21
	s_mul_hi_u32 s1, s0, 0x3800
	s_mulk_i32 s0, 0x3800
	s_lshl_b32 s16, s72, 1
	v_lshlrev_b32_e32 v132, 1, v22
	v_lshlrev_b32_e32 v22, 2, v20
	v_subrev_u32_e32 v23, 32, v15
	v_mov_b64_e32 v[20:21], s[0:1]
	v_subrev_u32_e32 v24, 64, v15
	v_add_u32_e32 v125, 0, v14
	v_add3_u32 v134, v14, v22, s44
	v_mad_i64_i32 v[14:15], s[0:1], s16, v23, v[20:21]
	v_mad_i64_i32 v[20:21], s[0:1], s16, v24, v[20:21]
	v_mul_u32_u24_e32 v27, 0x90, v0
	v_lshlrev_b32_e32 v0, 4, v113
	v_lshl_add_u64 v[22:23], v[14:15], 0, v[18:19]
	v_lshl_add_u64 v[14:15], v[14:15], 0, v[16:17]
	v_lshl_add_u64 v[18:19], v[20:21], 0, v[18:19]
	v_lshl_add_u64 v[16:17], v[20:21], 0, v[16:17]
	v_or_b32_e32 v126, 0x9f, v111
	v_mul_u32_u24_e32 v127, 0x90, v123
	v_mov_b32_e32 v3, v2
	v_mov_b32_e32 v4, v2
	v_mov_b32_e32 v5, v2
	v_mov_b32_e32 v6, v2
	v_mov_b32_e32 v7, v2
	v_mov_b32_e32 v8, v2
	v_mov_b32_e32 v9, v2
	v_mov_b32_e32 v10, v2
	v_mov_b32_e32 v11, v2
	v_mov_b32_e32 v12, v2
	v_mov_b32_e32 v13, v2
	v_add3_u32 v130, v125, v27, v0
	s_lshl_b32 s16, s72, 7
	v_lshl_add_u64 v[114:115], s[34:35], 0, v[22:23]
	v_lshl_add_u64 v[116:117], s[34:35], 0, v[14:15]
	v_lshl_add_u64 v[118:119], s[34:35], 0, v[18:19]
	v_lshl_add_u64 v[120:121], s[34:35], 0, v[16:17]
	v_mov_b32_e32 v14, v2
	v_mov_b32_e32 v15, v2
	v_mov_b32_e32 v16, v2
	v_mov_b32_e32 v17, v2
	v_mov_b32_e32 v18, v2
	v_mov_b32_e32 v19, v2
	v_mov_b32_e32 v20, v2
	v_mov_b32_e32 v21, v2
	v_mov_b32_e32 v22, v2
	v_mov_b32_e32 v23, v2
	v_mov_b32_e32 v24, v2
	v_mov_b32_e32 v25, v2
	v_mov_b32_e32 v26, v2
	v_mov_b32_e32 v27, v2
	v_mov_b32_e32 v28, v2
	v_mov_b32_e32 v29, v2
	v_mov_b32_e32 v30, v2
	v_mov_b32_e32 v31, v2
	v_mov_b32_e32 v32, v2
	v_mov_b32_e32 v33, v2
	s_waitcnt vmcnt(0) lgkmcnt(0)
	ds_write_b32 v137, v136
	v_and_b32_e32 v140, 0x80, v174
	v_cmp_eq_u32_e32 vcc, 0, v140
	s_and_saveexec_b64 s[22:23], vcc
	ds_write_b32 v137, v139 offset:1024
	s_or_b64 exec, exec, s[22:23]
	s_and_b64 vcc, exec, s[40:41]
	s_cbranch_vccnz .Lbp_nosink
	v_mul_f32_e32 v133, 0x3fb8aa3b, v138
.Lbp_nosink:
	s_cmp_eq_u32 s65, 0
	s_cselect_b32 s0, 0x4800, 0
	v_add_u32_e32 v254, s0, v130
	ds_write_b128 v254, v[82:85]
	ds_write_b128 v254, v[86:89] offset:9216
	ds_write_b128 v254, v[90:93] offset:4608
	ds_write_b128 v254, v[94:97] offset:13824
	s_branch .LBB0_214
